# GEMM7 second round: each leftover unit shared by two workgroups split by row halves (idle waves skip MFMA and epilogue)
# speedup vs baseline: 1.0679x; 1.0096x over previous
.LBB0_2299:
	s_cmp_lt_i32 s50, 13
	s_cselect_b64 s[0:1], -1, 0
	s_and_b64 s[10:11], s[0:1], s[4:5]
	s_andn2_b64 vcc, exec, s[10:11]
	s_cbranch_vccnz .LBB0_2338
	s_mov_b32 s101, 0
	v_readfirstlane_b32 s99, v179
	s_lshr_b32 s99, s99, 2
	s_cmpk_lt_i32 s2, 0x110
	s_cselect_b64 s[4:5], -1, 0
	s_cmpk_gt_i32 s2, 0x10f
	v_readfirstlane_b32 s0, v178
	s_waitcnt lgkmcnt(0)
	s_barrier
	s_cbranch_scc1 .LBB0_2302
	s_ashr_i32 s1, s2, 31
	s_lshr_b32 s1, s1, 29
	s_add_i32 s1, s2, s1
	s_ashr_i32 s3, s1, 3
	s_and_b32 s1, s1, -8
	s_sub_i32 s1, s2, s1
	s_cmp_lt_i32 s1, 0
	s_cselect_b32 s6, 35, 34
	s_mul_i32 s1, s1, s6
	s_add_i32 s1, s1, s3
	s_ashr_i32 s3, s1, 31
	s_lshr_b32 s3, s3, 27
	s_add_i32 s3, s1, s3
	s_ashr_i32 s6, s3, 5
	s_lshl_b32 s8, s6, 3
	s_sub_i32 s6, 0x44, s8
	s_min_u32 s9, s6, 8
	s_andn2_b32 s3, s3, 31
	s_sub_i32 s1, s1, s3
	v_cvt_f32_ubyte0_e32 v3, s9
	v_cvt_f32_i32_e32 v2, s1
	v_rcp_iflag_f32_e32 v4, v3
	s_ashr_i32 s3, s1, 30
	s_or_b32 s3, s3, 1
	v_mul_f32_e32 v4, v2, v4
	v_trunc_f32_e32 v4, v4
	v_fma_f32 v2, -v4, v3, v2
	v_cvt_i32_f32_e32 v4, v4
	v_cmp_ge_f32_e64 s[6:7], |v2|, v3
	s_and_b64 s[6:7], s[6:7], exec
	s_cselect_b32 s3, s3, 0
	v_readfirstlane_b32 s6, v4
	s_add_i32 s3, s6, s3
	s_sext_i32_i8 s62, s3
	s_mul_i32 s3, s3, s9
	s_sub_i32 s1, s1, s3
	s_sext_i32_i8 s1, s1
	s_add_i32 s63, s8, s1

.LBB0_2308:
	s_add_i32 s40, s40, 1
	s_mul_i32 s0, s40, s41
	s_mul_hi_u32 s1, s40, s57
	s_add_i32 s1, s1, s0
	s_mul_i32 s0, s40, s57
	s_add_u32 s6, s0, s2
	s_addc_u32 s7, s1, s42
	s_mov_b32 s100, s101
	s_mov_b32 s101, 0
	s_cmp_eq_u32 s48, 0x100
	s_cbranch_scc0 .Lsplit12_done
	s_cmp_eq_u32 s40, 1
	s_cbranch_scc0 .Lsplit12_done
	s_cmp_lt_u32 s2, 16
	s_cbranch_scc0 .Lsplit12_helper
	s_mov_b32 s101, 2
	s_branch .Lsplit12_done
.Lsplit12_helper:
	s_cmp_lt_u32 s2, 32
	s_cbranch_scc0 .Lsplit12_done
	s_sub_u32 s6, s6, 16
	s_mov_b32 s101, 1
.Lsplit12_done:
	s_sub_u32 s98, s100, 1
	v_cmp_gt_i64_e32 vcc, s[6:7], v[168:169]
	v_cmp_lt_i64_e64 s[8:9], s[6:7], v[166:167]
	s_cbranch_vccnz .LBB0_2310
	s_ashr_i32 s0, s6, 31
	s_lshr_b32 s0, s0, 29
	s_add_i32 s0, s6, s0
	s_ashr_i32 s1, s0, 3
	s_and_b32 s0, s0, -8
	s_sub_i32 s0, s6, s0
	s_cmp_lt_i32 s0, 0
	s_cselect_b32 s6, 35, 34
	s_mul_i32 s0, s0, s6
	s_add_i32 s0, s0, s1
	s_ashr_i32 s1, s0, 31
	s_lshr_b32 s1, s1, 27
	s_add_i32 s1, s0, s1
	s_ashr_i32 s6, s1, 5
	s_lshl_b32 s6, s6, 3
	s_sub_i32 s7, 0x44, s6
	s_min_i32 s7, s7, 8
	s_abs_i32 s22, s7
	v_cvt_f32_u32_e32 v2, s22
	s_sub_i32 s28, 0, s22
	s_andn2_b32 s1, s1, 31
	s_sub_i32 s0, s0, s1
	v_rcp_iflag_f32_e32 v2, v2
	s_abs_i32 s1, s0
	s_xor_b32 s23, s0, s7
	s_ashr_i32 s23, s23, 31
	v_mul_f32_e32 v2, 0x4f7ffffe, v2
	v_cvt_u32_f32_e32 v2, v2
	s_nop 0
	v_readfirstlane_b32 s29, v2
	s_mul_i32 s28, s28, s29
	s_mul_hi_u32 s28, s29, s28
	s_add_i32 s29, s29, s28
	s_mul_hi_u32 s28, s1, s29
	s_mul_i32 s29, s28, s22
	s_sub_i32 s1, s1, s29
	s_add_i32 s33, s28, 1
	s_sub_i32 s29, s1, s22
	s_cmp_ge_u32 s1, s22
	s_cselect_b32 s28, s33, s28
	s_cselect_b32 s1, s29, s1
	s_add_i32 s29, s28, 1
	s_cmp_ge_u32 s1, s22
	s_cselect_b32 s1, s29, s28
	s_xor_b32 s1, s1, s23
	s_sub_i32 s60, s1, s23
	s_mul_i32 s1, s60, s7
	s_sub_i32 s0, s0, s1
	s_add_i32 s61, s6, s0

.LBB0_2315:
	ds_read_b128 v[130:133], v186
	ds_read_b128 v[134:137], v186 offset:1024
	ds_read_b128 v[138:141], v186 offset:2048
	ds_read_b128 v[142:145], v186 offset:3072
	ds_read_b128 v[146:149], v187
	ds_read_b128 v[150:153], v187 offset:1024
	ds_read_b128 v[170:173], v187 offset:2048
	ds_read_b128 v[174:177], v187 offset:3072
	s_add_u32 s0, s24, 0xfff50080
	s_addc_u32 s1, s25, -1
	s_cmp_eq_u32 s66, 40
	s_cselect_b32 s29, s9, s1
	s_cselect_b32 s28, s8, s0
	s_cselect_b32 s27, s23, s65
	s_cselect_b32 s26, s22, s64
	v_lshl_add_u64 v[218:219], s[24:25], 0, v[162:163]
	s_add_i32 m0, s36, 0xc000
	ds_read_b128 v[180:183], v188
	ds_read_b128 v[190:193], v188 offset:1024
	ds_read_b128 v[194:197], v188 offset:2048
	ds_read_b128 v[198:201], v188 offset:3072
	ds_read_b128 v[202:205], v188 offset:4096
	ds_read_b128 v[206:209], v188 offset:5120
	ds_read_b128 v[210:213], v188 offset:6144
	ds_read_b128 v[214:217], v188 offset:7168
	global_load_lds_dwordx4 v[218:219], off
	v_lshl_add_u64 v[218:219], s[24:25], 0, v[164:165]
	s_add_i32 m0, s36, 0xe000
	s_nop 0
	global_load_lds_dwordx4 v[218:219], off
	s_waitcnt vmcnt(8)
	s_waitcnt lgkmcnt(0)
	s_barrier
	s_cmp_eq_u32 s99, s98
	s_cbranch_scc1 .Lsplit12_mma0
	s_setprio 1
	s_waitcnt lgkmcnt(0)
	v_mfma_f32_16x16x32_bf16 v[126:129], v[130:133], v[180:183], v[126:129]
	v_mfma_f32_16x16x32_bf16 v[122:125], v[138:141], v[180:183], v[122:125]
	v_mfma_f32_16x16x32_bf16 v[110:113], v[130:133], v[194:197], v[110:113]
	v_mfma_f32_16x16x32_bf16 v[106:109], v[138:141], v[194:197], v[106:109]
	v_mfma_f32_16x16x32_bf16 v[94:97], v[130:133], v[202:205], v[94:97]
	v_mfma_f32_16x16x32_bf16 v[90:93], v[138:141], v[202:205], v[90:93]
	v_mfma_f32_16x16x32_bf16 v[78:81], v[130:133], v[210:213], v[78:81]
	v_mfma_f32_16x16x32_bf16 v[74:77], v[138:141], v[210:213], v[74:77]
	v_mfma_f32_16x16x32_bf16 v[126:129], v[134:137], v[190:193], v[126:129]
	v_mfma_f32_16x16x32_bf16 v[122:125], v[142:145], v[190:193], v[122:125]
	v_mfma_f32_16x16x32_bf16 v[110:113], v[134:137], v[198:201], v[110:113]
	v_mfma_f32_16x16x32_bf16 v[106:109], v[142:145], v[198:201], v[106:109]
	v_mfma_f32_16x16x32_bf16 v[94:97], v[134:137], v[206:209], v[94:97]
	v_mfma_f32_16x16x32_bf16 v[90:93], v[142:145], v[206:209], v[90:93]
	v_mfma_f32_16x16x32_bf16 v[78:81], v[134:137], v[214:217], v[78:81]
	v_mfma_f32_16x16x32_bf16 v[74:77], v[142:145], v[214:217], v[74:77]
	s_setprio 0
	s_setprio 1
	v_mfma_f32_16x16x32_bf16 v[118:121], v[146:149], v[180:183], v[118:121]
	v_mfma_f32_16x16x32_bf16 v[114:117], v[170:173], v[180:183], v[114:117]
	v_mfma_f32_16x16x32_bf16 v[102:105], v[146:149], v[194:197], v[102:105]
	v_mfma_f32_16x16x32_bf16 v[98:101], v[170:173], v[194:197], v[98:101]
	v_mfma_f32_16x16x32_bf16 v[86:89], v[146:149], v[202:205], v[86:89]
	v_mfma_f32_16x16x32_bf16 v[82:85], v[170:173], v[202:205], v[82:85]
	v_mfma_f32_16x16x32_bf16 v[70:73], v[146:149], v[210:213], v[70:73]
	v_mfma_f32_16x16x32_bf16 v[66:69], v[170:173], v[210:213], v[66:69]
	v_mfma_f32_16x16x32_bf16 v[118:121], v[150:153], v[190:193], v[118:121]
	v_mfma_f32_16x16x32_bf16 v[114:117], v[174:177], v[190:193], v[114:117]
	v_mfma_f32_16x16x32_bf16 v[102:105], v[150:153], v[198:201], v[102:105]
	v_mfma_f32_16x16x32_bf16 v[98:101], v[174:177], v[198:201], v[98:101]
	v_mfma_f32_16x16x32_bf16 v[86:89], v[150:153], v[206:209], v[86:89]
	v_mfma_f32_16x16x32_bf16 v[82:85], v[174:177], v[206:209], v[82:85]
	v_mfma_f32_16x16x32_bf16 v[70:73], v[150:153], v[214:217], v[70:73]
	v_mfma_f32_16x16x32_bf16 v[66:69], v[174:177], v[214:217], v[66:69]
	s_setprio 0
.Lsplit12_mma0:
	s_barrier
	s_add_i32 s0, s58, s35
	v_lshl_add_u64 v[218:219], s[26:27], 0, v[156:157]
	s_mov_b32 m0, s0
	ds_read_b128 v[180:183], v188 offset:16384
	ds_read_b128 v[190:193], v188 offset:17408
	ds_read_b128 v[194:197], v188 offset:18432
	ds_read_b128 v[198:201], v188 offset:19456
	ds_read_b128 v[202:205], v188 offset:20480
	ds_read_b128 v[206:209], v188 offset:21504
	ds_read_b128 v[210:213], v188 offset:22528
	ds_read_b128 v[214:217], v188 offset:23552
	global_load_lds_dwordx4 v[218:219], off
	s_add_i32 m0, s0, 0x2000
	s_add_u32 s0, s26, 0xb0000
	v_lshl_add_u64 v[220:221], s[26:27], 0, v[160:161]
	s_addc_u32 s1, s27, 0
	s_add_i32 s33, s59, s35
	global_load_lds_dwordx4 v[220:221], off
	v_lshl_add_u64 v[222:223], s[0:1], 0, v[156:157]
	s_mov_b32 m0, s33
	v_lshl_add_u64 v[224:225], s[28:29], 0, v[158:159]
	global_load_lds_dwordx4 v[222:223], off
	v_lshl_add_u64 v[222:223], s[0:1], 0, v[160:161]
	s_add_i32 m0, s33, 0x2000
	s_nop 0
	global_load_lds_dwordx4 v[222:223], off
	v_lshl_add_u64 v[222:223], s[28:29], 0, v[154:155]
	s_mov_b32 m0, s36
	s_nop 0
	global_load_lds_dwordx4 v[222:223], off
	s_mov_b32 m0, s37
	s_nop 0
	global_load_lds_dwordx4 v[224:225], off
	s_waitcnt vmcnt(8)
	s_waitcnt lgkmcnt(0)
	s_barrier
	s_cmp_eq_u32 s99, s98
	s_cbranch_scc1 .Lsplit12_mma1
	s_setprio 1
	s_waitcnt lgkmcnt(0)
	v_mfma_f32_16x16x32_bf16 v[62:65], v[130:133], v[180:183], v[62:65]
	v_mfma_f32_16x16x32_bf16 v[58:61], v[138:141], v[180:183], v[58:61]
	v_mfma_f32_16x16x32_bf16 v[46:49], v[130:133], v[194:197], v[46:49]
	v_mfma_f32_16x16x32_bf16 v[42:45], v[138:141], v[194:197], v[42:45]
	v_mfma_f32_16x16x32_bf16 v[30:33], v[130:133], v[202:205], v[30:33]
	v_mfma_f32_16x16x32_bf16 v[26:29], v[138:141], v[202:205], v[26:29]
	v_mfma_f32_16x16x32_bf16 v[14:17], v[130:133], v[210:213], v[14:17]
	v_mfma_f32_16x16x32_bf16 v[10:13], v[138:141], v[210:213], v[10:13]
	v_mfma_f32_16x16x32_bf16 v[62:65], v[134:137], v[190:193], v[62:65]
	v_mfma_f32_16x16x32_bf16 v[58:61], v[142:145], v[190:193], v[58:61]
	v_mfma_f32_16x16x32_bf16 v[46:49], v[134:137], v[198:201], v[46:49]
	v_mfma_f32_16x16x32_bf16 v[42:45], v[142:145], v[198:201], v[42:45]
	v_mfma_f32_16x16x32_bf16 v[30:33], v[134:137], v[206:209], v[30:33]
	v_mfma_f32_16x16x32_bf16 v[26:29], v[142:145], v[206:209], v[26:29]
	v_mfma_f32_16x16x32_bf16 v[14:17], v[134:137], v[214:217], v[14:17]
	v_mfma_f32_16x16x32_bf16 v[10:13], v[142:145], v[214:217], v[10:13]
	s_setprio 0
	s_setprio 1
	v_mfma_f32_16x16x32_bf16 v[54:57], v[146:149], v[180:183], v[54:57]
	v_mfma_f32_16x16x32_bf16 v[50:53], v[170:173], v[180:183], v[50:53]
	v_mfma_f32_16x16x32_bf16 v[38:41], v[146:149], v[194:197], v[38:41]
	v_mfma_f32_16x16x32_bf16 v[34:37], v[170:173], v[194:197], v[34:37]
	v_mfma_f32_16x16x32_bf16 v[22:25], v[146:149], v[202:205], v[22:25]
	v_mfma_f32_16x16x32_bf16 v[18:21], v[170:173], v[202:205], v[18:21]
	v_mfma_f32_16x16x32_bf16 v[6:9], v[146:149], v[210:213], v[6:9]
	v_mfma_f32_16x16x32_bf16 v[2:5], v[170:173], v[210:213], v[2:5]
	v_mfma_f32_16x16x32_bf16 v[54:57], v[150:153], v[190:193], v[54:57]
	v_mfma_f32_16x16x32_bf16 v[50:53], v[174:177], v[190:193], v[50:53]
	v_mfma_f32_16x16x32_bf16 v[38:41], v[150:153], v[198:201], v[38:41]
	v_mfma_f32_16x16x32_bf16 v[34:37], v[174:177], v[198:201], v[34:37]
	v_mfma_f32_16x16x32_bf16 v[22:25], v[150:153], v[206:209], v[22:25]
	v_mfma_f32_16x16x32_bf16 v[18:21], v[174:177], v[206:209], v[18:21]
	v_mfma_f32_16x16x32_bf16 v[6:9], v[150:153], v[214:217], v[6:9]
	v_mfma_f32_16x16x32_bf16 v[2:5], v[174:177], v[214:217], v[2:5]
	s_setprio 0
.Lsplit12_mma1:
	s_barrier
	s_add_i32 s33, 0, 0x18000
	s_add_i32 s52, 0, 0x1c000
	v_add_u32_e32 v142, s33, v184
	v_add_u32_e32 v174, s52, v184
	ds_read_b128 v[130:133], v142
	ds_read_b128 v[134:137], v142 offset:1024
	ds_read_b128 v[138:141], v142 offset:2048
	ds_read_b128 v[142:145], v142 offset:3072
	ds_read_b128 v[146:149], v174
	ds_read_b128 v[150:153], v174 offset:1024
	ds_read_b128 v[170:173], v174 offset:2048
	ds_read_b128 v[174:177], v174 offset:3072
	s_add_u32 s0, s28, 0xb0000
	s_addc_u32 s1, s29, 0
	s_mov_b32 m0, s38
	v_lshl_add_u64 v[226:227], s[0:1], 0, v[154:155]
	ds_read_b128 v[180:183], v188 offset:32768
	ds_read_b128 v[190:193], v188 offset:33792
	ds_read_b128 v[194:197], v188 offset:34816
	ds_read_b128 v[198:201], v188 offset:35840
	ds_read_b128 v[202:205], v188 offset:36864
	ds_read_b128 v[206:209], v188 offset:37888
	ds_read_b128 v[210:213], v188 offset:38912
	ds_read_b128 v[214:217], v188 offset:39936
	global_load_lds_dwordx4 v[226:227], off
	v_lshl_add_u64 v[226:227], s[0:1], 0, v[158:159]
	s_mov_b32 m0, s39
	s_nop 0
	global_load_lds_dwordx4 v[226:227], off
	s_waitcnt vmcnt(8)
	s_waitcnt lgkmcnt(0)
	s_barrier
	s_cmp_eq_u32 s99, s98
	s_cbranch_scc1 .Lsplit12_mma2
	s_setprio 1
	s_waitcnt lgkmcnt(0)
	v_mfma_f32_16x16x32_bf16 v[126:129], v[130:133], v[180:183], v[126:129]
	v_mfma_f32_16x16x32_bf16 v[122:125], v[138:141], v[180:183], v[122:125]
	v_mfma_f32_16x16x32_bf16 v[110:113], v[130:133], v[194:197], v[110:113]
	v_mfma_f32_16x16x32_bf16 v[106:109], v[138:141], v[194:197], v[106:109]
	v_mfma_f32_16x16x32_bf16 v[94:97], v[130:133], v[202:205], v[94:97]
	v_mfma_f32_16x16x32_bf16 v[90:93], v[138:141], v[202:205], v[90:93]
	v_mfma_f32_16x16x32_bf16 v[78:81], v[130:133], v[210:213], v[78:81]
	v_mfma_f32_16x16x32_bf16 v[74:77], v[138:141], v[210:213], v[74:77]
	v_mfma_f32_16x16x32_bf16 v[126:129], v[134:137], v[190:193], v[126:129]
	v_mfma_f32_16x16x32_bf16 v[122:125], v[142:145], v[190:193], v[122:125]
	v_mfma_f32_16x16x32_bf16 v[110:113], v[134:137], v[198:201], v[110:113]
	v_mfma_f32_16x16x32_bf16 v[106:109], v[142:145], v[198:201], v[106:109]
	v_mfma_f32_16x16x32_bf16 v[94:97], v[134:137], v[206:209], v[94:97]
	v_mfma_f32_16x16x32_bf16 v[90:93], v[142:145], v[206:209], v[90:93]
	v_mfma_f32_16x16x32_bf16 v[78:81], v[134:137], v[214:217], v[78:81]
	v_mfma_f32_16x16x32_bf16 v[74:77], v[142:145], v[214:217], v[74:77]
	s_setprio 0
	s_setprio 1
	v_mfma_f32_16x16x32_bf16 v[118:121], v[146:149], v[180:183], v[118:121]
	v_mfma_f32_16x16x32_bf16 v[114:117], v[170:173], v[180:183], v[114:117]
	v_mfma_f32_16x16x32_bf16 v[102:105], v[146:149], v[194:197], v[102:105]
	v_mfma_f32_16x16x32_bf16 v[98:101], v[170:173], v[194:197], v[98:101]
	v_mfma_f32_16x16x32_bf16 v[86:89], v[146:149], v[202:205], v[86:89]
	v_mfma_f32_16x16x32_bf16 v[82:85], v[170:173], v[202:205], v[82:85]
	v_mfma_f32_16x16x32_bf16 v[70:73], v[146:149], v[210:213], v[70:73]
	v_mfma_f32_16x16x32_bf16 v[66:69], v[170:173], v[210:213], v[66:69]
	v_mfma_f32_16x16x32_bf16 v[118:121], v[150:153], v[190:193], v[118:121]
	v_mfma_f32_16x16x32_bf16 v[114:117], v[174:177], v[190:193], v[114:117]
	v_mfma_f32_16x16x32_bf16 v[102:105], v[150:153], v[198:201], v[102:105]
	v_mfma_f32_16x16x32_bf16 v[98:101], v[174:177], v[198:201], v[98:101]
	v_mfma_f32_16x16x32_bf16 v[86:89], v[150:153], v[206:209], v[86:89]
	v_mfma_f32_16x16x32_bf16 v[82:85], v[174:177], v[206:209], v[82:85]
	v_mfma_f32_16x16x32_bf16 v[70:73], v[150:153], v[214:217], v[70:73]
	v_mfma_f32_16x16x32_bf16 v[66:69], v[174:177], v[214:217], v[66:69]
	s_setprio 0
.Lsplit12_mma2:
	s_barrier
	s_add_i32 s0, s33, s35
	v_lshl_add_u64 v[218:219], v[218:219], 0, s[18:19]
	s_mov_b32 m0, s0
	ds_read_b128 v[180:183], v188 offset:49152
	ds_read_b128 v[190:193], v188 offset:50176
	ds_read_b128 v[194:197], v188 offset:51200
	ds_read_b128 v[198:201], v188 offset:52224
	ds_read_b128 v[202:205], v188 offset:53248
	ds_read_b128 v[206:209], v188 offset:54272
	ds_read_b128 v[210:213], v188 offset:55296
	ds_read_b128 v[214:217], v188 offset:56320
	global_load_lds_dwordx4 v[218:219], off
	s_add_i32 m0, s0, 0x2000
	s_add_u32 s0, s26, 0xb0080
	v_lshl_add_u64 v[218:219], v[220:221], 0, s[18:19]
	s_addc_u32 s1, s27, 0
	s_add_i32 s26, s52, s35
	global_load_lds_dwordx4 v[218:219], off
	v_lshl_add_u64 v[218:219], s[0:1], 0, v[156:157]
	s_mov_b32 m0, s26
	s_nop 0
	global_load_lds_dwordx4 v[218:219], off
	v_lshl_add_u64 v[218:219], s[0:1], 0, v[160:161]
	s_add_i32 m0, s26, 0x2000
	s_nop 0
	global_load_lds_dwordx4 v[218:219], off
	v_lshl_add_u64 v[218:219], v[222:223], 0, s[18:19]
	s_mov_b32 m0, s43
	s_nop 0
	global_load_lds_dwordx4 v[218:219], off
	v_lshl_add_u64 v[218:219], v[224:225], 0, s[18:19]
	s_mov_b32 m0, s56
	s_nop 0
	global_load_lds_dwordx4 v[218:219], off
	s_waitcnt vmcnt(8)
	s_waitcnt lgkmcnt(0)
	s_barrier
	s_cmp_eq_u32 s99, s98
	s_cbranch_scc1 .Lsplit12_mma3
	s_setprio 1
	s_waitcnt lgkmcnt(0)
	v_mfma_f32_16x16x32_bf16 v[62:65], v[130:133], v[180:183], v[62:65]
	v_mfma_f32_16x16x32_bf16 v[58:61], v[138:141], v[180:183], v[58:61]
	v_mfma_f32_16x16x32_bf16 v[46:49], v[130:133], v[194:197], v[46:49]
	v_mfma_f32_16x16x32_bf16 v[42:45], v[138:141], v[194:197], v[42:45]
	v_mfma_f32_16x16x32_bf16 v[30:33], v[130:133], v[202:205], v[30:33]
	v_mfma_f32_16x16x32_bf16 v[26:29], v[138:141], v[202:205], v[26:29]
	v_mfma_f32_16x16x32_bf16 v[14:17], v[130:133], v[210:213], v[14:17]
	v_mfma_f32_16x16x32_bf16 v[10:13], v[138:141], v[210:213], v[10:13]
	v_mfma_f32_16x16x32_bf16 v[62:65], v[134:137], v[190:193], v[62:65]
	v_mfma_f32_16x16x32_bf16 v[58:61], v[142:145], v[190:193], v[58:61]
	v_mfma_f32_16x16x32_bf16 v[46:49], v[134:137], v[198:201], v[46:49]
	v_mfma_f32_16x16x32_bf16 v[42:45], v[142:145], v[198:201], v[42:45]
	v_mfma_f32_16x16x32_bf16 v[30:33], v[134:137], v[206:209], v[30:33]
	v_mfma_f32_16x16x32_bf16 v[26:29], v[142:145], v[206:209], v[26:29]
	v_mfma_f32_16x16x32_bf16 v[14:17], v[134:137], v[214:217], v[14:17]
	v_mfma_f32_16x16x32_bf16 v[10:13], v[142:145], v[214:217], v[10:13]
	s_setprio 0
	s_setprio 1
	v_mfma_f32_16x16x32_bf16 v[54:57], v[146:149], v[180:183], v[54:57]
	v_mfma_f32_16x16x32_bf16 v[50:53], v[170:173], v[180:183], v[50:53]
	v_mfma_f32_16x16x32_bf16 v[38:41], v[146:149], v[194:197], v[38:41]
	v_mfma_f32_16x16x32_bf16 v[34:37], v[170:173], v[194:197], v[34:37]
	v_mfma_f32_16x16x32_bf16 v[22:25], v[146:149], v[202:205], v[22:25]
	v_mfma_f32_16x16x32_bf16 v[18:21], v[170:173], v[202:205], v[18:21]
	v_mfma_f32_16x16x32_bf16 v[6:9], v[146:149], v[210:213], v[6:9]
	v_mfma_f32_16x16x32_bf16 v[2:5], v[170:173], v[210:213], v[2:5]
	v_mfma_f32_16x16x32_bf16 v[54:57], v[150:153], v[190:193], v[54:57]
	v_mfma_f32_16x16x32_bf16 v[50:53], v[174:177], v[190:193], v[50:53]
	v_mfma_f32_16x16x32_bf16 v[38:41], v[150:153], v[198:201], v[38:41]
	v_mfma_f32_16x16x32_bf16 v[34:37], v[174:177], v[198:201], v[34:37]
	v_mfma_f32_16x16x32_bf16 v[22:25], v[150:153], v[206:209], v[22:25]
	v_mfma_f32_16x16x32_bf16 v[18:21], v[174:177], v[206:209], v[18:21]
	v_mfma_f32_16x16x32_bf16 v[6:9], v[150:153], v[214:217], v[6:9]
	v_mfma_f32_16x16x32_bf16 v[2:5], v[174:177], v[214:217], v[2:5]
	s_setprio 0
.Lsplit12_mma3:
	s_barrier
	s_add_i32 s66, s66, 2
	s_add_u32 s24, s24, 0x100
	s_addc_u32 s25, s25, 0
	s_add_u32 s64, s64, 0x100
	s_addc_u32 s65, s65, 0
	s_cmp_gt_u32 s66, 41
	s_cbranch_scc0 .LBB0_2315
	s_and_b64 vcc, exec, s[20:21]
	s_cbranch_vccz .LBB0_2318
	s_barrier
.LBB0_2318:
	s_cmp_eq_u32 s99, s98
	s_cbranch_scc1 .Lsplit12_epi
	v_lshl_add_u32 v172, s63, 8, v1
	v_lshl_or_b32 v170, s62, 8, v185
	v_ashrrev_i32_e32 v173, 31, v172
	v_ashrrev_i32_e32 v171, 31, v170
	v_lshlrev_b64 v[130:131], 11, v[172:173]
	v_lshl_add_u64 v[130:131], s[14:15], 0, v[130:131]
	v_lshlrev_b64 v[174:175], 1, v[170:171]
	v_lshl_add_u64 v[130:131], v[130:131], 0, v[174:175]
	global_load_dwordx4 v[192:195], v[130:131], off
	global_load_dwordx4 v[196:199], v[130:131], off offset:256
	v_or_b32_e32 v182, 16, v172
	v_or_b32_e32 v180, 32, v172
	v_or_b32_e32 v176, 48, v172
	v_ashrrev_i32_e32 v183, 31, v182
	v_ashrrev_i32_e32 v181, 31, v180
	v_ashrrev_i32_e32 v177, 31, v176
	v_lshlrev_b64 v[130:131], 11, v[182:183]
	v_lshlrev_b64 v[132:133], 11, v[180:181]
	v_lshlrev_b64 v[134:135], 11, v[176:177]
	v_lshl_add_u64 v[130:131], s[14:15], 0, v[130:131]
	v_lshl_add_u64 v[132:133], s[14:15], 0, v[132:133]
	v_lshl_add_u64 v[134:135], s[14:15], 0, v[134:135]
	v_lshl_add_u64 v[130:131], v[130:131], 0, v[174:175]
	v_lshl_add_u64 v[132:133], v[132:133], 0, v[174:175]
	v_lshl_add_u64 v[190:191], v[134:135], 0, v[174:175]
	global_load_dwordx4 v[150:153], v[130:131], off
	global_load_dwordx4 v[146:149], v[130:131], off offset:256
	global_load_dwordx4 v[142:145], v[132:133], off
	global_load_dwordx4 v[138:141], v[132:133], off offset:256
	global_load_dwordx4 v[134:137], v[190:191], off
	s_nop 0
	global_load_dwordx4 v[130:133], v[190:191], off offset:256
	v_and_b32_e32 v191, 64, v189
	v_xor_b32_e32 v190, 16, v189
	v_add_u32_e32 v191, 64, v191
	v_xor_b32_e32 v200, 32, v189
	v_cmp_lt_i32_e32 vcc, v190, v191
	s_waitcnt vmcnt(0)
	v_lshlrev_b32_e32 v202, 16, v194
	v_cndmask_b32_e32 v190, v189, v190, vcc
	v_cmp_lt_i32_e32 vcc, v200, v191
	v_and_b32_e32 v203, 0xffff0000, v194
	v_and_b32_e32 v201, 0xffff0000, v192
	v_cndmask_b32_e32 v191, v189, v200, vcc
	v_lshlrev_b32_e32 v200, 16, v192
	v_lshlrev_b32_e32 v192, 16, v193
	v_and_b32_e32 v193, 0xffff0000, v193
	v_lshlrev_b32_e32 v194, 16, v195
	v_and_b32_e32 v195, 0xffff0000, v195
	v_lshlrev_b32_e32 v206, 16, v198
	v_and_b32_e32 v207, 0xffff0000, v198
	v_pk_add_f32 v[122:123], v[122:123], v[202:203]
	v_lshlrev_b32_e32 v198, 16, v199
	v_and_b32_e32 v199, 0xffff0000, v199
	v_pk_add_f32 v[128:129], v[128:129], v[192:193]
	v_pk_add_f32 v[126:127], v[126:127], v[200:201]
	v_pk_add_f32 v[124:125], v[124:125], v[194:195]
	v_pk_add_f32 v[192:193], v[114:115], v[206:207]
	v_mul_f32_e32 v114, v122, v122
	v_mul_f32_e32 v115, v123, v123
	v_pk_add_f32 v[194:195], v[116:117], v[198:199]
	v_mul_f32_e32 v116, v124, v124
	v_fmac_f32_e32 v114, v126, v126
	v_fmac_f32_e32 v115, v127, v127
	v_lshlrev_b32_e32 v204, 16, v196
	v_and_b32_e32 v205, 0xffff0000, v196
	v_lshlrev_b32_e32 v196, 16, v197
	v_and_b32_e32 v197, 0xffff0000, v197
	v_mul_f32_e32 v117, v125, v125
	v_fmac_f32_e32 v116, v128, v128
	v_add_f32_e32 v114, v114, v115
	v_pk_add_f32 v[120:121], v[120:121], v[196:197]
	v_pk_add_f32 v[118:119], v[118:119], v[204:205]
	v_mul_f32_e32 v196, v192, v192
	v_fmac_f32_e32 v117, v129, v129
	v_add_f32_e32 v114, v116, v114
	v_mul_f32_e32 v197, v193, v193
	v_fmac_f32_e32 v196, v118, v118
	v_add_f32_e32 v114, v117, v114
	v_mul_f32_e32 v198, v194, v194
	v_fmac_f32_e32 v197, v119, v119
	v_add_f32_e32 v114, v196, v114
	v_mul_f32_e32 v199, v195, v195
	v_fmac_f32_e32 v198, v120, v120
	v_add_f32_e32 v114, v197, v114
	v_add_f32_e32 v114, v198, v114
	v_fmac_f32_e32 v199, v121, v121
	v_lshlrev_b32_e32 v190, 2, v190
	v_add_f32_e32 v115, v199, v114
	ds_bpermute_b32 v198, v190, v115
	v_lshlrev_b64 v[116:117], 12, v[172:173]
	v_lshlrev_b32_e32 v114, 2, v191
	v_lshl_add_u64 v[116:117], s[44:45], 0, v[116:117]
	v_lshl_add_u64 v[196:197], v[170:171], 2, v[116:117]
	s_waitcnt lgkmcnt(0)
	v_add_f32_e32 v115, v115, v198
	ds_bpermute_b32 v116, v114, v115
	global_store_dwordx4 v[196:197], v[126:129], off
	global_store_dwordx4 v[196:197], v[122:125], off offset:16
	global_store_dwordx4 v[196:197], v[118:121], off offset:512
	global_store_dwordx4 v[196:197], v[192:195], off offset:528
	s_and_saveexec_b64 s[24:25], s[4:5]
	s_cbranch_execz .LBB0_2320
	v_lshl_add_u64 v[118:119], v[172:173], 2, s[16:17]
	s_waitcnt lgkmcnt(0)
	v_add_f32_e32 v115, v115, v116
	global_atomic_add_f32 v[118:119], v115, off

.Lsplit12_epi:
	s_and_b64 vcc, exec, s[6:7]
	s_mov_b64 s[6:7], -1
	s_cbranch_vccnz .LBB0_2307
	s_andn2_b64 vcc, exec, s[12:13]
	s_cbranch_vccnz .LBB0_2306
	s_barrier
	s_branch .LBB0_2306
